# v12: v11 + GLU GEMM tiles of phase 4/14 all taken (4 each) by the workgroups whose diff-attention unit is head 0 (they finish attention first)
# speedup vs baseline: 1.0298x; 1.0045x over previous
; template <class Epi, class Sched, bool ALIGN_EPI = false, bool SP2 = false>
; __device__ __forceinline__ void gemm_phase(PG8_LAS unsigned char* lds, const Gemm g, const Sched& S, const Epi& E) {
;     int tid_ = threadIdx.x; asm volatile("" : "+v"(tid_));
;     const int tid = tid_, wid = __builtin_amdgcn_readfirstlane(tid >> 6), lane = tid & 63, wr = wid >> 2, wc = wid & 3, fr = lane & 15, fq = lane >> 4;
;     const int K = g.K, nt = K / BK;
;     unsigned voffA[2], voffB[2];
; #pragma unroll
;     for (int i = 0; i < 2; ++i) { int R, C; stage_rc(tid * 16 + i * 8192, R, C); const int Rb = Epi::PERM ? ((R & ~31) + perm32(R & 31)) : R;
;         voffA[i] = (unsigned)(R * g.lda + C) * 2u; voffB[i] = (unsigned)(Rb * g.ldb + C) * 2u; }
;     const size_t kstep = (size_t)(BK * 2);
;     const size_t hstepA = (size_t)HALF * g.lda * 2, hstepB = (size_t)HALF * g.ldb * 2;
;     const size_t tstepA = 2 * hstepA, tstepB = 2 * hstepB;
;     const unsigned ldsw = (unsigned)wid * 1024u;
;     const int aoff = lds_byte(wr * 64 + fr, fq * 8), boff = lds_byte(wc * 32 + fr, fq * 8);
;     ...
;     Unit cur, nxt; int ui = 0;
;     if (!S.next(0, cur)) return;
;     f32x4 acc[2][2][4][2];
; #pragma unroll
;     for (int a = 0; a < 2; ++a)
; #pragma unroll
;         for (int b = 0; b < 2; ++b)
; #pragma unroll
;             for (int m = 0; m < 4; ++m)
; #pragma unroll
;                 for (int n = 0; n < 2; ++n) acc[a][b][m][n] = (f32x4){0.f, 0.f, 0.f, 0.f};
;     bf16x8 At[4][2], B0[2][2], B1[2][2];
;     const char* cA = (const char*)g.A + (size_t)cur.pm * tstepA; const char* cB = (const char*)g.Bt + (size_t)cur.pn * tstepB;
;     S.a_ready(cur);
;     if constexpr (SP2) {
;         PG8_STAGE(PG8_SB(0, 0), cB, voffB); PG8_STAGE(PG8_SB(0, 1), cB + hstepB, voffB); PG8_STAGE(PG8_SA(0, 0), cA, voffA); PG8_STAGE(PG8_SA(0, 1), cA + hstepA, voffA);
;         if (wr == 1) PG8_BAR;
;         PG8_WAIT_V(2); PG8_BAR;
;         PG8_STAGE(PG8_SB(1, 0), cB + kstep, voffB); PG8_STAGE(PG8_SA(1, 0), cA + kstep, voffA); PG8_STAGE(PG8_SB(1, 1), cB + hstepB + kstep, voffB);
;         PG8_WAIT_V(6); PG8_BAR;
;     } else {
;         PG8_STAGE(PG8_SB(0, 0), cB, voffB); PG8_STAGE(PG8_SA(0, 0), cA, voffA); PG8_STAGE(PG8_SB(0, 1), cB + hstepB, voffB); PG8_STAGE(PG8_SA(0, 1), cA + hstepA, voffA);
;         if (wr == 1) PG8_BAR;
;         PG8_WAIT_V(4); PG8_BAR;
.LBB0_662:
	s_bfe_u32 s100, s33, 0x20004
	s_cmp_lg_u32 s100, 0
	s_cbranch_scc1 .Lglu_none_g1
	s_lshr_b32 s100, s33, 6
	s_lshl_b32 s100, s100, 4
	s_and_b32 s101, s33, 15
	s_or_b32 s100, s100, s101
	s_mov_b32 s101, 64
	s_branch .Lglu_go_g1
.Lglu_none_g1:
	s_movk_i32 s100, 0x100
	s_movk_i32 s101, 0x100
.Lglu_go_g1:
	s_movk_i32 s22, 0xca0
	s_movk_i32 s5, 0x200
	s_movk_i32 s3, 0x400
	s_movk_i32 s6, 0x200
	s_barrier
	s_ashr_i32 s4, s3, 31
	s_lshr_b32 s4, s4, 24
	s_add_i32 s3, s3, s4
	s_ashr_i32 s34, s3, 8
	s_lshl_b32 s4, s34, 6
	v_mov_b32_e32 v14, v1
	s_cmp_ge_i32 s100, s4
	v_readfirstlane_b32 s38, v14
	s_cbranch_scc1 .LBB0_683
	v_lshlrev_b32_e32 v2, 4, v14
	v_add_u32_e32 v3, 0x2000, v2
	v_ashrrev_i32_e32 v4, 31, v3
	v_lshrrev_b32_e32 v4, 22, v4
	v_add_u32_e32 v4, v3, v4
	v_ashrrev_i32_e32 v4, 10, v4
	v_mul_i32_i24_e32 v5, 0x400, v4
	v_sub_u32_e32 v3, v3, v5
	v_lshrrev_b32_e32 v5, 4, v3
	v_bitop3_b32 v3, v5, v3, 32 bitop3:0x6c
	v_ashrrev_i32_e32 v5, 31, v3
	v_lshrrev_b32_e32 v5, 26, v5
	v_add_u32_e32 v5, v3, v5
	v_lshlrev_b32_e32 v7, 3, v4
	v_ashrrev_i32_e32 v6, 6, v5
	v_and_b32_e32 v7, -16, v7
	v_lshlrev_b32_e32 v4, 5, v4
	v_add_u32_e32 v7, v6, v7
	v_and_b32_e32 v15, 32, v4
	v_and_b32_e32 v4, 0xc0, v5
	v_and_b32_e32 v6, 3, v6
	s_mov_b32 s35, 0x7fffffe0
	v_lshrrev_b32_e32 v8, 2, v7
	v_lshlrev_b32_e32 v9, 1, v7
	v_sub_u32_e32 v3, v3, v4
	v_mov_b32_e32 v4, 1
	v_and_or_b32 v6, v7, s35, v6
	v_and_b32_e32 v8, 4, v8
	v_and_b32_e32 v9, 24, v9
	v_ashrrev_i16_sdwa v3, v4, sext(v3) dst_sel:DWORD dst_unused:UNUSED_PAD src0_sel:DWORD src1_sel:BYTE_0
	v_or3_b32 v6, v6, v8, v9
	v_bfe_i32 v16, v3, 0, 16
	v_mul_lo_u32 v6, v6, s6
	v_add_u32_e32 v3, v15, v16
	v_mul_lo_u32 v17, v7, s22
	s_waitcnt vmcnt(11)
	v_add_lshl_u32 v130, v6, v3, 1
	v_add_lshl_u32 v132, v3, v17, 1
	v_bfe_i32 v3, v14, 27, 1
	v_lshrrev_b32_e32 v3, 22, v3
	v_add_u32_e32 v3, v2, v3
	v_and_b32_e32 v3, 0xfffffc00, v3
	v_sub_u32_e32 v2, v2, v3
	v_lshrrev_b32_e32 v3, 4, v2
	v_ashrrev_i32_e32 v6, 31, v14
	v_bitop3_b32 v2, v3, v2, 32 bitop3:0x6c
	v_lshrrev_b32_e32 v6, 26, v6
	v_ashrrev_i32_e32 v3, 31, v2
	v_add_u32_e32 v6, v14, v6
	s_add_u32 s3, s16, 0x1540
	v_lshrrev_b32_e32 v3, 26, v3
	v_ashrrev_i32_e32 v6, 6, v6
	s_addc_u32 s27, s17, 0
	v_add_u32_e32 v3, v2, v3
	v_lshlrev_b32_e32 v7, 3, v6
	s_add_u32 s54, s16, 0xdc20000
	v_ashrrev_i32_e32 v5, 6, v3
	v_and_b32_e32 v7, -16, v7
	s_addc_u32 s55, s17, 0
	v_add_u32_e32 v7, v5, v7
	v_and_b32_e32 v5, 3, v5
	s_ashr_i32 s58, s100, 31
	v_and_or_b32 v5, v7, s35, v5
	s_lshr_b32 s35, s58, 29
	s_add_i32 s35, s100, s35
	s_ashr_i32 s36, s38, 6
	s_ashr_i32 s23, s22, 31
	s_ashr_i32 s7, s6, 31
	s_lshl_b32 s57, s34, 3
	s_ashr_i32 s39, s35, 3
	s_and_b32 s35, s35, -8
	s_ashr_i32 s37, s38, 8
	s_lshl_b64 s[8:9], s[22:23], 8
	s_lshl_b64 s[10:11], s[6:7], 8
	s_lshl_b64 s[18:19], s[22:23], 9
	s_lshl_b64 s[20:21], s[6:7], 9
	s_lshl_b32 s56, s36, 10
	s_sub_i32 s35, s100, s35
	s_or_b32 s59, s57, 1
	s_cmp_lt_i32 s35, 0
	v_and_b32_e32 v3, 0xc0, v3
	s_cselect_b32 s40, s59, s57
	s_abs_i32 s60, s57
	v_sub_u32_e32 v2, v2, v3
	v_cvt_f32_u32_e32 v3, s60
	s_mul_i32 s35, s40, s35
	s_sub_i32 s40, 0, s60
	s_add_i32 s35, s35, s39
	v_rcp_iflag_f32_e32 v3, v3
	s_ashr_i32 s39, s35, 31
	s_bfe_i32 s61, s34, 0x1001c
	s_xor_b32 s34, s39, s61
	v_mul_f32_e32 v3, 0x4f7ffffe, v3
	v_cvt_u32_f32_e32 v3, v3
	s_abs_i32 s39, s35
	v_lshrrev_b32_e32 v8, 2, v7
	v_lshlrev_b32_e32 v9, 1, v7
	v_readfirstlane_b32 s62, v3
	s_mul_i32 s40, s40, s62
	s_mul_hi_u32 s40, s62, s40
	s_add_i32 s62, s62, s40
	s_mul_hi_u32 s40, s39, s62
	s_mul_i32 s41, s40, s60
	s_sub_i32 s39, s39, s41
	s_add_i32 s41, s40, 1
	s_sub_i32 s42, s39, s60
	s_cmp_ge_u32 s39, s60
	s_cselect_b32 s40, s41, s40
	s_cselect_b32 s39, s42, s39
	s_add_i32 s41, s40, 1
	s_cmp_ge_u32 s39, s60
	s_cselect_b32 s39, s41, s40
	s_xor_b32 s39, s39, s34
	s_sub_i32 s34, s39, s34
	s_lshl_b32 s39, s34, 3
	s_sub_i32 s40, 64, s39
	s_min_i32 s40, s40, 8
	s_abs_i32 s41, s40
	v_cvt_f32_u32_e32 v3, s41
	v_and_b32_e32 v8, 4, v8
	v_and_b32_e32 v9, 24, v9
	v_lshlrev_b32_e32 v6, 5, v6
	v_ashrrev_i16_sdwa v2, v4, sext(v2) dst_sel:DWORD dst_unused:UNUSED_PAD src0_sel:DWORD src1_sel:BYTE_0
	v_or3_b32 v5, v5, v8, v9
	v_and_b32_e32 v18, 32, v6
	v_bfe_i32 v19, v2, 0, 16
	v_mul_lo_u32 v5, v5, s6
	v_add_u32_e32 v2, v18, v19
	v_mul_lo_u32 v20, v7, s22
	s_waitcnt vmcnt(10)
	v_add_lshl_u32 v134, v5, v2, 1
	v_add_lshl_u32 v136, v2, v20, 1
	v_rcp_iflag_f32_e32 v2, v3
	s_sub_i32 s43, 0, s41
	s_mul_i32 s34, s34, s57
	s_sub_i32 s34, s35, s34
	v_mul_f32_e32 v2, 0x4f7ffffe, v2
	v_cvt_u32_f32_e32 v2, v2
	s_abs_i32 s42, s34
	s_xor_b32 s35, s34, s40
	s_ashr_i32 s35, s35, 31
	v_readfirstlane_b32 s44, v2
	s_mul_i32 s43, s43, s44
	s_mul_hi_u32 s43, s44, s43
	s_add_i32 s44, s44, s43
	s_mul_hi_u32 s43, s42, s44
	s_mul_i32 s44, s43, s41
	s_sub_i32 s42, s42, s44
	s_add_i32 s44, s43, 1
	s_sub_i32 s45, s42, s41
	s_cmp_ge_u32 s42, s41
	s_cselect_b32 s43, s44, s43
	s_cselect_b32 s42, s45, s42
	s_add_i32 s44, s43, 1
	s_cmp_ge_u32 s42, s41
	s_cselect_b32 s41, s44, s43
	s_xor_b32 s41, s41, s35
	s_sub_i32 s79, s41, s35
	s_mul_i32 s35, s79, s40
	s_sub_i32 s34, s34, s35
	s_add_i32 s80, s34, s39
	s_ashr_i32 s34, s80, 31
	s_lshr_b64 s[22:23], s[22:23], 23
	s_mul_i32 s34, s18, s34
	s_mul_hi_u32 s35, s18, s80
	s_ashr_i32 s23, s79, 31
	s_add_i32 s34, s35, s34
	s_mul_i32 s23, s20, s23
	s_mul_hi_u32 s35, s20, s79
	s_lshr_b64 s[6:7], s[6:7], 23
	s_mul_i32 s22, s22, s80
	s_add_i32 s23, s35, s23
	s_mul_i32 s6, s6, s79
	s_add_i32 s34, s34, s22
	s_add_i32 s23, s23, s6
	s_mul_i32 s6, s20, s79
	s_add_u32 s50, s54, s6
	s_addc_u32 s51, s55, s23
	s_add_i32 s63, s56, 0
	s_add_i32 m0, s63, 0x10000
	s_mul_i32 s22, s18, s80
	global_load_lds_dwordx4 v134, s[50:51]
	s_add_i32 m0, s63, 0x12000
	s_add_u32 s6, s50, s10
	global_load_lds_dwordx4 v130, s[50:51]
	s_addc_u32 s7, s51, s11
	s_add_i32 m0, s63, 0x14000
	v_mov_b32_e32 v135, 0
	global_load_lds_dwordx4 v134, s[6:7]
	s_add_i32 m0, s63, 0x16000
	s_add_u32 s52, s3, s22
	s_addc_u32 s53, s27, s34
	s_add_i32 s64, s63, 0x2000
	global_load_lds_dwordx4 v130, s[6:7]
	s_mov_b32 m0, s63
	s_add_u32 s22, s52, s8
	global_load_lds_dwordx4 v136, s[52:53]
	s_mov_b32 m0, s64
	s_addc_u32 s23, s53, s9
	s_add_i32 s65, s63, 0x4000
	global_load_lds_dwordx4 v132, s[52:53]
	s_mov_b32 m0, s65
	s_add_i32 s66, s63, 0x6000
	global_load_lds_dwordx4 v136, s[22:23]
	s_mov_b32 m0, s66
	v_mov_b32_e32 v131, v135
	global_load_lds_dwordx4 v132, s[22:23]
	v_mov_b32_e32 v137, v135
	v_mov_b32_e32 v133, v135
	s_cmp_eq_u32 s37, 1
	s_mov_b32 s67, 0
	v_lshl_add_u64 v[10:11], s[50:51], 0, v[134:135]
	v_lshl_add_u64 v[6:7], s[50:51], 0, v[130:131]
	v_lshl_add_u64 v[4:5], s[6:7], 0, v[134:135]
	v_lshl_add_u64 v[2:3], s[6:7], 0, v[130:131]
	v_lshl_add_u64 v[8:9], s[52:53], 0, v[136:137]
	s_cselect_b64 s[22:23], -1, 0
	s_cmp_lg_u32 s37, 1
	v_lshl_add_u64 v[12:13], s[52:53], 0, v[132:133]
	s_cbranch_scc1 .LBB0_665
	s_barrier
; #define PG8_WAIT_V(n) asm volatile("s_waitcnt vmcnt(" #n ")" ::: "memory")
; #define PG8_BAR __builtin_amdgcn_s_barrier()
; template <class Epi, class Sched, bool ALIGN_EPI = false, bool SP2 = false>
; __device__ __forceinline__ void gemm_phase(PG8_LAS unsigned char* lds, const Gemm g, const Sched& S, const Epi& E) {
;     ...
;     const size_t kstep = (size_t)(BK * 2);
;     const size_t hstepA = (size_t)HALF * g.lda * 2, hstepB = (size_t)HALF * g.ldb * 2;
;     const size_t tstepA = 2 * hstepA, tstepB = 2 * hstepB;
;     const unsigned ldsw = (unsigned)wid * 1024u;
;     const int aoff = lds_byte(wr * 64 + fr, fq * 8), boff = lds_byte(wc * 32 + fr, fq * 8);
;     ...
;     Unit cur, nxt; int ui = 0;
;     if (!S.next(0, cur)) return;
;     f32x4 acc[2][2][4][2];
; #pragma unroll
;     for (int a = 0; a < 2; ++a)
; #pragma unroll
;         for (int b = 0; b < 2; ++b)
; #pragma unroll
;             for (int m = 0; m < 4; ++m)
; #pragma unroll
;                 for (int n = 0; n < 2; ++n) acc[a][b][m][n] = (f32x4){0.f, 0.f, 0.f, 0.f};
;     bf16x8 At[4][2], B0[2][2], B1[2][2];
;     const char* cA = (const char*)g.A + (size_t)cur.pm * tstepA; const char* cB = (const char*)g.Bt + (size_t)cur.pn * tstepB;
;     S.a_ready(cur);
;     if constexpr (SP2) {
;         PG8_STAGE(PG8_SB(0, 0), cB, voffB); PG8_STAGE(PG8_SB(0, 1), cB + hstepB, voffB); PG8_STAGE(PG8_SA(0, 0), cA, voffA); PG8_STAGE(PG8_SA(0, 1), cA + hstepA, voffA);
;         if (wr == 1) PG8_BAR;
;         PG8_WAIT_V(2); PG8_BAR;
;         PG8_STAGE(PG8_SB(1, 0), cB + kstep, voffB); PG8_STAGE(PG8_SA(1, 0), cA + kstep, voffA); PG8_STAGE(PG8_SB(1, 1), cB + hstepB + kstep, voffB);
;         PG8_WAIT_V(6); PG8_BAR;
;     } else {
;         PG8_STAGE(PG8_SB(0, 0), cB, voffB); PG8_STAGE(PG8_SA(0, 0), cA, voffA); PG8_STAGE(PG8_SB(0, 1), cB + hstepB, voffB); PG8_STAGE(PG8_SA(0, 1), cA + hstepA, voffA);
;         if (wr == 1) PG8_BAR;
;         PG8_WAIT_V(4); PG8_BAR;
;         PG8_STAGE(PG8_SB(1, 0), cB + kstep, voffB); PG8_STAGE(PG8_SA(1, 0), cA + kstep, voffA); PG8_STAGE(PG8_SB(1, 1), cB + hstepB + kstep, voffB);
;         PG8_WAIT_V(6); PG8_BAR;
;     }
;     for (;;) {
;         const bool has_next = S.next(ui + 1, nxt);
;         const char* nA = has_next ? (const char*)g.A + (size_t)nxt.pm * tstepA : cA; const char* nB = has_next ? (const char*)g.Bt + (size_t)nxt.pn * tstepB : cB;
.LBB0_665:
	s_add_u32 s16, s16, 0xbd00000
	s_mov_b64 s[34:35], 0x80
	s_addc_u32 s17, s17, 0
	s_add_i32 m0, s63, 0x18000
	v_lshl_add_u64 v[10:11], v[10:11], 0, s[34:35]
	s_waitcnt vmcnt(2)
	s_barrier
	global_load_lds_dwordx4 v[10:11], off
	v_lshl_add_u64 v[6:7], v[6:7], 0, s[34:35]
	s_add_i32 m0, s63, 0x1a000
	s_add_i32 s68, s63, 0x8000
	global_load_lds_dwordx4 v[6:7], off
	v_lshl_add_u64 v[6:7], v[8:9], 0, s[34:35]
	s_mov_b32 m0, s68
	s_add_i32 s69, s63, 0xa000
	global_load_lds_dwordx4 v[6:7], off
	v_lshl_add_u64 v[6:7], v[12:13], 0, s[34:35]
	s_mov_b32 m0, s69
	v_lshl_add_u64 v[4:5], v[4:5], 0, s[34:35]
	global_load_lds_dwordx4 v[6:7], off
	s_add_i32 m0, s63, 0x1c000
	v_lshl_add_u64 v[2:3], v[2:3], 0, s[34:35]
	global_load_lds_dwordx4 v[4:5], off
	s_add_i32 m0, s63, 0x1e000
	s_ashr_i32 s6, s5, 31
	global_load_lds_dwordx4 v[2:3], off
	v_lshrrev_b32_e32 v3, 1, v14
	v_and_b32_e32 v3, 24, v3
	v_and_b32_e32 v2, 15, v14
	s_lshr_b32 s6, s6, 26
	v_lshlrev_b32_e32 v4, 1, v3
	s_add_i32 s6, s5, s6
	v_lshl_or_b32 v146, s37, 6, v2
	v_lshl_or_b32 v2, v2, 6, v4
	v_lshlrev_b32_e32 v4, 2, v14
	s_ashr_i32 s70, s6, 6
	s_lshl_b32 s6, s37, 13
	v_and_b32_e32 v4, 32, v4
	v_bitop3_b32 v5, v2, s6, v4 bitop3:0xde
	s_lshl_b32 s6, s36, 5
	s_and_b32 s6, s6, 0x60
	s_lshl_b32 s7, s6, 7
	v_bitop3_b32 v147, v2, s7, v4 bitop3:0xde
	s_cmp_gt_i32 s5, 63
	v_add_u32_e32 v2, v17, v15
	s_cselect_b64 s[36:37], -1, 0
	s_add_i32 s71, s70, -2
	v_or_b32_e32 v148, s6, v3
	v_add_lshl_u32 v2, v2, v16, 1
	v_mov_b32_e32 v3, v135
	s_waitcnt vmcnt(6)
	s_cmpk_lt_u32 s38, 0x100
	s_waitcnt vmcnt(0)
	v_lshl_add_u64 v[138:139], s[8:9], 0, v[2:3]
	v_add_u32_e32 v2, v20, v18
	s_cselect_b64 s[38:39], -1, 0
	s_ashr_i32 s5, s4, 31
	v_add_lshl_u32 v2, v2, v19, 1
	s_add_i32 s75, 0, 0x10000
	s_add_i32 s76, 0, 0x14000
	s_ashr_i32 s74, s101, 31
	v_lshl_add_u64 v[140:141], s[8:9], 0, v[2:3]
	v_mov_b64_e32 v[142:143], s[4:5]
	v_add_u32_e32 v149, s75, v147
	v_add_u32_e32 v150, s76, v147
	v_add_u32_e32 v151, 0, v5
	s_mov_b64 s[40:41], 0x20000
	s_mov_b64 s[42:43], 0x24000
	s_mov_b64 s[44:45], 0x28000
	s_mov_b64 s[46:47], 0x2c000
	s_barrier
	s_branch .LBB0_668

;     __host__ __device__ bool next(int i, Unit& u) const {
;         const long L = (long)i * G + c; if (L >= nwg) return false;
;         int wgid = (int)L; { const int q = nwg / NXCD, r = nwg % NXCD, xcd = wgid % NXCD, off = wgid / NXCD; wgid = (xcd < r ? xcd * (q + 1) : r * (q + 1) + (xcd - r) * q) + off; }
;         const int nig = WGM * nN, gid = wgid / nig, fm = gid * WGM, gsz = (nM - fm) < WGM ? (nM - fm) : WGM;
;         u.pm = fm + ((wgid % nig) % gsz); u.pn = (wgid % nig) / gsz; return true;
;     }
.LBB0_668:
	s_add_i32 s67, s67, 1
	s_mul_i32 s4, s67, s74
	s_mul_hi_u32 s5, s67, s101
	s_add_i32 s5, s5, s4
	s_mul_i32 s4, s67, s101
	s_add_u32 s4, s4, s100
	s_addc_u32 s5, s5, s58
	v_cmp_ge_i64_e32 vcc, s[4:5], v[142:143]
	v_cmp_lt_i64_e64 s[6:7], s[4:5], v[142:143]
	s_cbranch_vccnz .LBB0_670
	s_ashr_i32 s5, s4, 31
	s_lshr_b32 s5, s5, 29
	s_add_i32 s5, s4, s5
	s_ashr_i32 s48, s5, 3
	s_and_b32 s5, s5, -8
	s_sub_i32 s4, s4, s5
	s_cmp_lt_i32 s4, 0
	s_cselect_b32 s5, s59, s57
	s_mul_i32 s4, s5, s4
	s_add_i32 s4, s4, s48
	s_abs_i32 s48, s4
	s_mul_hi_u32 s49, s48, s62
	s_mul_i32 s77, s49, s60
	s_ashr_i32 s5, s4, 31
	s_sub_i32 s48, s48, s77
	s_xor_b32 s5, s5, s61
	s_add_i32 s77, s49, 1
	s_sub_i32 s78, s48, s60
	s_cmp_ge_u32 s48, s60
	s_cselect_b32 s49, s77, s49
	s_cselect_b32 s48, s78, s48
	s_add_i32 s77, s49, 1
	s_cmp_ge_u32 s48, s60
	s_cselect_b32 s48, s77, s49
	s_xor_b32 s48, s48, s5
	s_sub_i32 s5, s48, s5
	s_lshl_b32 s48, s5, 3
	s_sub_i32 s49, 64, s48
	s_min_i32 s49, s49, 8
	s_abs_i32 s77, s49
	v_cvt_f32_u32_e32 v2, s77
	s_sub_i32 s81, 0, s77
	s_mul_i32 s5, s5, s57
	s_sub_i32 s4, s4, s5
	v_rcp_iflag_f32_e32 v2, v2
	s_abs_i32 s78, s4
	s_xor_b32 s5, s4, s49
	s_ashr_i32 s5, s5, 31
	v_mul_f32_e32 v2, 0x4f7ffffe, v2
	v_cvt_u32_f32_e32 v2, v2
	s_nop 0
	v_readfirstlane_b32 s82, v2
	s_mul_i32 s81, s81, s82
	s_mul_hi_u32 s81, s82, s81
	s_add_i32 s82, s82, s81
	s_mul_hi_u32 s81, s78, s82
	s_mul_i32 s82, s81, s77
	s_sub_i32 s78, s78, s82
	s_add_i32 s82, s81, 1
	s_sub_i32 s83, s78, s77
	s_cmp_ge_u32 s78, s77
	s_cselect_b32 s81, s82, s81
	s_cselect_b32 s78, s83, s78
	s_add_i32 s82, s81, 1
	s_cmp_ge_u32 s78, s77
	s_cselect_b32 s77, s82, s81
	s_xor_b32 s77, s77, s5
	s_sub_i32 s77, s77, s5
	s_mul_i32 s5, s77, s49
	s_sub_i32 s4, s4, s5
	s_add_i32 s78, s4, s48
